# best_final + P0 pass A/B boundary moved from item 6912 to 5632 (more weight-copy items on the workgroups without an adaLN item)
# speedup vs baseline: 1.0052x; 1.0052x over previous
.LBB0_84:
	s_andn2_b64 vcc, exec, s[0:1]
	s_cbranch_vccnz .LBB0_168
	s_cmpk_gt_i32 s85, 0x15ff
	s_cbranch_scc1 .LBB0_104
	v_lshrrev_b32_e32 v16, 5, v1
	v_lshlrev_b32_e32 v2, 2, v130
	v_and_b32_e32 v2, 0x7c, v2
	v_mul_u32_u24_e32 v6, 0x84, v16
	v_add3_u32 v17, s3, v2, v6
	v_lshlrev_b32_e32 v6, 3, v1
	v_mov_b32_e32 v3, 0
	v_and_b32_e32 v6, 56, v6
	v_mul_u32_u24_e32 v8, 0x84, v6
	v_lshlrev_b32_e32 v6, 1, v6
	v_mov_b32_e32 v7, v3
	v_lshl_add_u64 v[14:15], s[66:67], 0, v[6:7]
	s_mov_b64 s[0:1], 0x1700000
	v_lshl_add_u64 v[6:7], v[14:15], 0, s[0:1]
	s_mov_b64 s[0:1], 0x2600000
	v_lshl_add_u64 v[10:11], v[14:15], 0, s[0:1]
	s_mov_b64 s[0:1], 0xc00000
	v_lshrrev_b32_e32 v18, 3, v1
	v_lshl_add_u64 v[14:15], v[14:15], 0, s[0:1]
	s_lshl_b32 s0, s85, 6
	v_lshlrev_b32_e32 v9, 2, v18
	s_waitcnt lgkmcnt(0)
	s_add_i32 s12, s0, 0x7fffea00
	s_lshl_b32 s0, s85, 1
	v_lshl_add_u64 v[4:5], s[20:21], 0, v[2:3]
	v_add3_u32 v19, s3, v8, v9
	v_or_b32_e32 v20, 8, v18
	v_or_b32_e32 v21, 16, v18
	v_or_b32_e32 v22, 24, v18
	v_lshl_add_u64 v[8:9], s[58:59], 0, v[2:3]
	v_lshl_add_u64 v[12:13], s[18:19], 0, v[2:3]
	s_lshl_b32 s10, s85, 5
	s_lshl_b32 s11, s84, 5
	s_lshl_b32 s13, s84, 6
	s_add_i32 s14, s0, 0x7fffd400
	s_lshl_b32 s15, s84, 1
	s_mov_b32 s1, 0
	s_movk_i32 s26, 0x7fff
	s_mov_b32 s27, 0xffff0000
	s_movk_i32 s28, 0x5800
	v_add_u32_e32 v23, 0x400, v17
	v_add_u32_e32 v24, 0x800, v17
	v_add_u32_e32 v25, 0xc00, v17
	v_add_u32_e32 v26, 0x1000, v17
	v_add_u32_e32 v27, 0x1400, v17
	v_add_u32_e32 v28, 0x1800, v17
	v_add_u32_e32 v29, 0x1c00, v17
	s_mov_b32 s29, s85
	s_branch .LBB0_89

.LBB0_88:
	s_add_i32 s29, s29, s84
	s_add_i32 s10, s10, s11
	s_add_i32 s12, s12, s13
	s_add_i32 s14, s14, s15
	s_cmpk_gt_i32 s29, 0x15ff
	s_cbranch_scc1 .LBB0_104

.LBB0_104:
	s_cmpk_gt_i32 s2, 0x8f
	s_cbranch_scc0 .LBB0_168
	s_add_i32 s88, s85, 0x1180
	s_cmpk_gt_i32 s88, 0x29ff
	s_cbranch_scc1 .LBB0_168
	v_lshrrev_b32_e32 v48, 5, v1
	s_movk_i32 s4, 0x84
	v_mov_b32_e32 v6, 0x108
	v_mad_u32_u24 v29, v48, s4, v6
	v_mov_b32_e32 v6, 0x210
	v_mad_u32_u24 v30, v48, s4, v6
	v_mov_b32_e32 v6, 0x420
	v_lshlrev_b32_e32 v2, 2, v130
	v_mad_u32_u24 v31, v48, s4, v6
	v_mov_b32_e32 v6, 0x630
	v_lshrrev_b32_e32 v50, 3, v1
	v_lshlrev_b32_e32 v1, 3, v1
	v_and_b32_e32 v2, 0x7c, v2
	v_mov_b32_e32 v3, 0
	v_mad_u32_u24 v32, v48, s4, v6
	v_mov_b32_e32 v6, 0x840
	v_and_b32_e32 v1, 56, v1
	v_add_u32_e32 v28, s3, v2
	v_mad_u32_u24 v33, v48, s4, v6
	v_lshlrev_b32_e32 v6, 1, v1
	v_mov_b32_e32 v7, v3
	v_mad_u32_u24 v49, v48, s4, v28
	v_lshl_add_u64 v[26:27], s[66:67], 0, v[6:7]
	s_mov_b64 s[4:5], 0x2400000
	v_lshl_add_u64 v[6:7], v[26:27], 0, s[4:5]
	s_mov_b64 s[4:5], 0x1d00000
	v_lshl_add_u64 v[10:11], v[26:27], 0, s[4:5]
	s_mov_b64 s[4:5], 0x3100000
	v_lshl_add_u64 v[14:15], v[26:27], 0, s[4:5]
	s_mov_b64 s[4:5], 0x1700000
	s_add_i32 s91, s84, 0xfffffb80
	v_lshl_add_u64 v[18:19], v[26:27], 0, s[4:5]
	s_mov_b64 s[4:5], 0x2600000
	s_waitcnt lgkmcnt(0)
	s_cmp_lg_u64 s[48:49], 0
	v_lshl_add_u64 v[22:23], v[26:27], 0, s[4:5]
	s_mov_b64 s[4:5], 0xc00000
	s_cselect_b64 s[0:1], -1, 0
	v_lshl_add_u64 v[26:27], v[26:27], 0, s[4:5]
	s_lshl_b32 s4, s88, 6
	v_lshl_add_u64 v[4:5], s[54:55], 0, v[2:3]
	v_mul_u32_u24_e32 v8, 0x84, v1
	v_lshlrev_b32_e32 v1, 2, v50
	v_lshl_add_u64 v[12:13], s[60:61], 0, v[2:3]
	v_lshl_add_u64 v[24:25], s[18:19], 0, v[2:3]
	s_add_i32 s93, s4, 0x7fffea00
	s_lshl_b32 s4, s88, 1
	s_movk_i32 s18, 0xf8b0
	s_movk_i32 s26, 0xf8b8
	s_movk_i32 s30, 0xf8c0
	s_movk_i32 s36, 0xf8c8
	s_movk_i32 s54, 0xf8d0
	s_movk_i32 s60, 0xf8d8
	s_movk_i32 s72, 0xf8e0
	s_movk_i32 s76, 0xf8e8
	s_movk_i32 s80, 0xf8f0
	s_movk_i32 s84, 0xf8f8
	v_add3_u32 v1, s3, v8, v1
	v_or_b32_e32 v51, 8, v50
	v_or_b32_e32 v52, 16, v50
	v_or_b32_e32 v53, 24, v50
	v_lshl_add_u64 v[8:9], s[40:41], 0, v[2:3]
	v_lshl_add_u64 v[16:17], s[20:21], 0, v[2:3]
	v_lshl_add_u64 v[20:21], s[58:59], 0, v[2:3]
	s_lshl_b32 s3, s88, 5
	s_lshl_b32 s92, s91, 5
	s_lshl_b32 s94, s91, 6
	s_add_i32 s95, s4, 0x7fffb000
	s_lshl_b32 s96, s91, 1
	s_mov_b32 s7, 0
	v_cndmask_b32_e64 v54, 0, 1, s[0:1]
	v_add_u32_e32 v55, v28, v30
	v_add_u32_e32 v56, v28, v32
	s_movk_i32 s97, 0x7fff
	s_mov_b32 s10, 0xffff0000
	s_mov_b32 s11, 0x4d000
	s_mov_b32 s12, 0x9a000
	v_add_u32_e32 v57, v28, v29
	v_add_u32_e32 v58, v28, v31
	v_add_u32_e32 v59, v28, v33
	s_movk_i32 s13, 0x5800
	s_mov_b64 s[14:15], 0xb0
	s_mov_b32 s19, -1
	s_mov_b64 s[20:21], 0xb8
	s_mov_b32 s27, -1
	s_mov_b64 s[28:29], 0xc0
	s_mov_b32 s31, -1
	s_mov_b64 s[34:35], 0xc8
	s_mov_b32 s37, -1
	s_mov_b64 s[40:41], 0xd0
	s_mov_b32 s55, -1
	s_mov_b64 s[58:59], 0xd8
	s_mov_b32 s61, -1
	s_mov_b64 s[70:71], 0xe0
	s_mov_b32 s73, -1
	s_mov_b64 s[74:75], 0xe8
	s_mov_b32 s77, -1
	s_mov_b64 s[78:79], 0xf0
	s_mov_b32 s81, -1
	s_mov_b64 s[82:83], 0xf8
	s_mov_b32 s85, -1
	s_branch .LBB0_109
